# WKV2: idle wave 2 prefetches record lines into L2 in 64KB bursts ahead of the two scan waves (progress published through LDS)
# speedup vs baseline: 1.0217x; 1.0139x over previous
; __device__ __forceinline__ void ph_wkv2(const Params& p, int jl, int lane, int wave) {
;     ...
;     const bool vres = jl == 1; const int ri = lane >> 4, cg = lane & 15;
;     bf16* YW = (bf16*)(p.ws + WS_YW);
;     const int fr = lane & 15, fq = lane >> 4;
;     const int gw = blockIdx.x * NWAVES + wave, NGW = gridDim.x * NWAVES;
;     for (int job = wave < 2 ? blockIdx.x * 2 + wave : BATCH * WH * 4; job < BATCH * WH * 4; job += gridDim.x * 2) {
;         const int it = job & 3, h = (job >> 2) & 15, seq = job >> 6, r0 = seq * TP;
;         const unsigned char* rec = p.ws + WS_REC + (size_t)((seq * WH + h) * WC_NCH) * REC_BYTES;
;         f32x4 Sacc[4];
; #pragma unroll
;         for (int jt = 0; jt < 4; ++jt) Sacc[jt] = (f32x4){0.f, 0.f, 0.f, 0.f};
;         struct WRec { v4u wa0, wa1, rp0, rp1, bk0, bk1, bk2, bk3, tm; v2u vv; f32x4 g0, g1, g2, g3; };
;         WRec RA, RB;
;     ...
;         static_assert(WC_NCH % 2 == 1, "chunk loop unrolled by two plus one");
;         WC_LOAD(RA, rec); WC_LOAD(RB, rec + REC_BYTES);
;         v2u ypk = (v2u){0u, 0u};
;         for (int c = 0; c + 1 < WC_NCH; c += 2) { WC_STEP(RA, RB, c); WC_STEP(RB, RA, c + 1); }
;         WC_STEP(RA, RB, WC_NCH - 1);
;         *(v2u*)(YW + (size_t)(r0 + WC_C * (WC_NCH - 1) + 4 * fq + (fr & 3)) * D + h * WN + 16 * it + (fr & 12)) = ypk;
;     ...
;         float* so = p.out + O_WKVP + ((((size_t)jl * BATCH + seq) * WH + h) * WN + 16 * it + fr) * WN + 4 * fq;
; #pragma unroll
;         for (int jt = 0; jt < 4; ++jt) *(f32x4*)(so + 16 * jt) = Sacc[jt];
.LBB0_127:
	s_cmp_gt_i32 s20, 10
	s_mov_b64 s[0:1], -1
	s_cbranch_scc0 .LBB0_192
	v_readlane_b32 s3, v255, 15
	s_cmp_gt_i32 s3, 1
	v_readlane_b32 s2, v252, 46
	s_waitcnt lgkmcnt(0)
	s_load_dword s28, s[88:89], 0x0
	s_cselect_b64 s[0:1], -1, 0
	s_add_i32 s2, s3, s2
	s_cmpk_gt_i32 s2, 0x1ff
	s_cselect_b64 s[4:5], -1, 0
	s_or_b64 s[0:1], s[0:1], s[4:5]
	v_lshrrev_b32_e32 v151, 4, v238
	v_and_b32_e32 v150, 15, v194
	s_and_b64 vcc, exec, s[0:1]
	s_cbranch_vccnz .LBB0_136
	v_readlane_b32 s0, v255, 13
	v_and_b32_e32 v0, 3, v194
	v_readlane_b32 s10, v252, 49
	s_lshr_b32 s0, s0, 6
	v_lshlrev_b32_e32 v152, 4, v238
	v_and_b32_e32 v160, 48, v194
	v_lshl_or_b32 v181, v151, 2, v0
	v_and_b32_e32 v2, 12, v194
	v_and_b32_e32 v3, 1, v194
	v_cmp_gt_u32_e64 s[6:7], 2, v0
	v_lshlrev_b32_e32 v0, 4, v151
	v_readlane_b32 s11, v252, 50
	v_readlane_b32 s1, v252, 46
	v_mov_b32_e32 v153, v1
	v_or_b32_e32 v154, 0x400, v152
	v_mov_b32_e32 v155, v1
	v_or_b32_e32 v156, 0x800, v152
	v_mov_b32_e32 v157, v1
	v_or_b32_e32 v158, 0xc00, v152
	v_mov_b32_e32 v159, v1
	v_mov_b32_e32 v161, v1
	v_or_b32_e32 v162, 64, v160
	v_mov_b32_e32 v163, v1
	v_or_b32_e32 v164, 0x80, v160
	v_mov_b32_e32 v165, v1
	v_or_b32_e32 v166, 0xc0, v160
	v_mov_b32_e32 v167, v1
	v_lshlrev_b32_e32 v180, 3, v238
	v_cmp_eq_u32_e64 s[4:5], 0, v3
	v_or_b32_e32 v182, 0x7f0, v181
	v_or_b32_e32 v183, 0x800, v181
	s_lshl_b32 s3, s69, 3
	s_waitcnt lgkmcnt(0)
	s_lshl_b32 s9, s28, 1
	v_lshl_add_u64 v[168:169], s[10:11], 0, v[0:1]
	s_add_i32 s10, s1, s0
	v_or_b32_e32 v184, 32, v181
	v_lshlrev_b32_e32 v170, 1, v2
	ds_write_b32 v1, v1
	s_branch .LBB0_131
.LBB0_130:
	s_waitcnt vmcnt(13)
	v_mov_b32_e32 v204, 0x1000
	s_mov_b64 s[14:15], exec
	s_mov_b64 exec, 1
	ds_write_b32 v1, v204
	s_mov_b64 exec, s[14:15]
	v_add_u32_e32 v54, s12, v182
	v_ashrrev_i32_e32 v55, 31, v54
	v_lshlrev_b64 v[54:55], 11, v[54:55]
	v_lshl_add_u64 v[54:55], s[34:35], 0, v[54:55]
	s_lshl_b32 s94, s13, 1
	v_lshl_add_u64 v[54:55], v[54:55], 0, s[94:95]
	s_lshl_b32 s0, s18, 1
	s_mov_b32 s1, s95
	v_lshl_add_u64 v[54:55], v[54:55], 0, s[0:1]
	v_mov_b32_e32 v171, v1
	v_lshl_add_u64 v[54:55], v[54:55], 0, v[170:171]
	global_store_dwordx2 v[54:55], v[30:31], off
	s_waitcnt vmcnt(2)
	v_mfma_f32_16x16x16_bf16 v[54:57], v[102:103], v[32:33], 0
	v_cvt_pk_bf16_f32 v63, v144, v145
	v_cvt_pk_bf16_f32 v62, v142, v143
	v_cvt_pk_bf16_f32 v65, v124, v125
	v_cvt_pk_bf16_f32 v64, v122, v123
	v_mfma_f32_16x16x16_bf16 v[58:61], v[104:105], v[32:33], 0
	s_nop 2
	v_add_f32_e64 v56, v56, 0
	v_add_f32_e64 v57, v57, 0
	v_pk_add_f32 v[54:55], v[54:55], 0 op_sel_hi:[1,0]
	v_cvt_pk_bf16_f32 v67, v120, v121
	v_cvt_pk_bf16_f32 v66, v118, v119
	v_mfma_f32_16x16x32_bf16 v[2:5], v[2:5], v[62:65], v[54:57]
	v_cvt_pk_bf16_f32 v69, v116, v117
	v_cvt_pk_bf16_f32 v68, v114, v115
	v_pk_add_f32 v[60:61], v[60:61], 0 op_sel_hi:[1,0]
	v_pk_add_f32 v[58:59], v[58:59], 0 op_sel_hi:[1,0]
	v_mfma_f32_16x16x32_bf16 v[2:5], v[10:13], v[66:69], v[2:5]
	s_nop 0
	v_mfma_f32_16x16x32_bf16 v[10:13], v[46:49], v[62:65], v[58:61]
	v_mfma_f32_16x16x32_bf16 v[10:13], v[42:45], v[66:69], v[10:13]
	s_nop 4
	v_cvt_pk_bf16_f32 v31, v4, v5
	v_cvt_pk_bf16_f32 v30, v2, v3
	s_nop 1
	v_mfma_f32_16x16x32_bf16 v[6:9], v[6:9], v[30:33], v[114:117]
	v_cndmask_b32_e64 v0, v10, v11, s[4:5]
	s_nop 1
	v_mov_b32_dpp v0, v0 quad_perm:[1,0,3,2] row_mask:0xf bank_mask:0xf bound_ctrl:1
	v_cndmask_b32_e64 v10, v0, v10, s[4:5]
	s_nop 2
	v_pk_mul_f32 v[6:7], v[18:19], v[6:7]
	v_cndmask_b32_e64 v18, v12, v13, s[4:5]
	v_cndmask_b32_e64 v0, v11, v0, s[4:5]
	v_mfma_f32_16x16x32_bf16 v[2:5], v[38:41], v[30:33], v[142:145]
	v_mov_b32_dpp v18, v18 quad_perm:[1,0,3,2] row_mask:0xf bank_mask:0xf bound_ctrl:1
	v_cndmask_b32_e64 v11, v18, v12, s[4:5]
	v_cndmask_b32_e64 v12, v13, v18, s[4:5]
	v_cndmask_b32_e64 v13, v10, v11, s[6:7]
	v_cndmask_b32_e64 v18, v0, v12, s[6:7]
	v_mfma_f32_16x16x32_bf16 v[26:29], v[26:29], v[30:33], v[122:125]
	v_mov_b32_dpp v13, v13 quad_perm:[2,3,0,1] row_mask:0xf bank_mask:0xf bound_ctrl:1
	v_mov_b32_dpp v18, v18 quad_perm:[2,3,0,1] row_mask:0xf bank_mask:0xf bound_ctrl:1
	v_cndmask_b32_e64 v11, v11, v13, s[6:7]
	v_cndmask_b32_e64 v12, v12, v18, s[6:7]
	v_cvt_pk_bf16_f32 v11, v11, v12
	v_add_u32_e32 v12, s12, v183
	v_cndmask_b32_e64 v10, v13, v10, s[6:7]
	v_ashrrev_i32_e32 v13, 31, v12
	v_lshlrev_b64 v[12:13], 11, v[12:13]
	v_lshl_add_u64 v[12:13], s[34:35], 0, v[12:13]
	v_lshl_add_u64 v[12:13], v[12:13], 0, s[94:95]
	v_lshl_add_u64 v[12:13], v[12:13], 0, s[0:1]
	s_ashr_i32 s1, s11, 31
	s_add_u32 s0, s11, s3
	v_cndmask_b32_e64 v0, v18, v0, s[6:7]
	s_addc_u32 s1, s1, 0
	v_cvt_pk_bf16_f32 v10, v10, v0
	v_lshl_add_u64 v[12:13], v[12:13], 0, v[170:171]
	s_lshl_b64 s[0:1], s[0:1], 10
	v_mfma_f32_16x16x32_bf16 v[14:17], v[14:17], v[30:33], v[118:121]
	global_store_dwordx2 v[12:13], v[10:11], off
	v_or_b32_e32 v0, s0, v150
	v_mov_b32_e32 v10, s18
	v_or3_b32 v11, s1, 0, 0
	v_or3_b32 v10, v0, s13, v10
	v_lshlrev_b64 v[10:11], 8, v[10:11]
	s_add_i32 s2, s2, s9
	s_sub_i32 s10, s10, s9
	v_pk_mul_f32 v[4:5], v[52:53], v[4:5]
	v_pk_mul_f32 v[2:3], v[50:51], v[2:3]
	v_lshl_add_u64 v[10:11], v[168:169], 0, v[10:11]
	s_cmpk_gt_i32 s2, 0x1ff
	v_pk_mul_f32 v[28:29], v[36:37], v[28:29]
	v_pk_mul_f32 v[26:27], v[34:35], v[26:27]
	v_pk_mul_f32 v[16:17], v[24:25], v[16:17]
	v_pk_mul_f32 v[14:15], v[22:23], v[14:15]
	v_pk_mul_f32 v[8:9], v[20:21], v[8:9]
	global_store_dwordx4 v[10:11], v[2:5], off
	global_store_dwordx4 v[10:11], v[26:29], off offset:64
	global_store_dwordx4 v[10:11], v[14:17], off offset:128
	global_store_dwordx4 v[10:11], v[6:9], off offset:192
	s_cbranch_scc1 .LBB0_136

; __device__ __forceinline__ void ph_wkv2(const Params& p, int jl, int lane, int wave) {
;     ...
;         static_assert(WC_NCH % 2 == 1, "chunk loop unrolled by two plus one");
;         WC_LOAD(RA, rec); WC_LOAD(RB, rec + REC_BYTES);
;         v2u ypk = (v2u){0u, 0u};
;         for (int c = 0; c + 1 < WC_NCH; c += 2) { WC_STEP(RA, RB, c); WC_STEP(RB, RA, c + 1); }
.LBB0_132:
	s_waitcnt vmcnt(15)
	v_mov_b32_e32 v204, s19
	s_mov_b64 s[14:15], exec
	s_mov_b64 exec, 1
	ds_write_b32 v1, v204
	s_mov_b64 exec, s[14:15]
	v_mfma_f32_16x16x16_bf16 v[146:149], v[102:103], v[32:33], 0
	v_cvt_pk_bf16_f32 v177, v144, v145
	v_cvt_pk_bf16_f32 v176, v142, v143
	v_cvt_pk_bf16_f32 v179, v124, v125
	v_cvt_pk_bf16_f32 v178, v122, v123
	v_cvt_pk_bf16_f32 v187, v120, v121
	s_nop 2
	v_pk_add_f32 v[148:149], v[148:149], 0 op_sel_hi:[1,0]
	v_pk_add_f32 v[146:147], v[146:147], 0 op_sel_hi:[1,0]
	v_cvt_pk_bf16_f32 v186, v118, v119
	v_cvt_pk_bf16_f32 v189, v116, v117
	v_mfma_f32_16x16x32_bf16 v[2:5], v[2:5], v[176:179], v[146:149]
	v_cvt_pk_bf16_f32 v188, v114, v115
	v_add_u32_e32 v94, -16, v174
	v_ashrrev_i32_e32 v95, 31, v94
	v_mfma_f32_16x16x32_bf16 v[2:5], v[10:13], v[186:189], v[2:5]
	v_lshlrev_b64 v[94:95], 11, v[94:95]
	v_lshl_add_u64 v[94:95], v[172:173], 0, v[94:95]
	global_store_dwordx2 v[94:95], v[30:31], off
	v_mfma_f32_16x16x16_bf16 v[102:105], v[104:105], v[32:33], 0
	s_mov_b32 s20, 0x46f9b000
	s_nop 2
	v_cvt_pk_bf16_f32 v31, v4, v5
	v_cvt_pk_bf16_f32 v30, v2, v3
	v_ashrrev_i32_e32 v175, 31, v174
	s_cmpk_gt_u32 s19, 0x7d
	v_mfma_f32_16x16x32_bf16 v[2:5], v[38:41], v[30:33], v[142:145]
	v_add_f32_e64 v104, v104, 0
	v_add_f32_e64 v105, v105, 0
	v_pk_add_f32 v[102:103], v[102:103], 0 op_sel_hi:[1,0]
	s_nop 1
	v_mfma_f32_16x16x32_bf16 v[10:13], v[46:49], v[176:179], v[102:105]
	s_nop 1
	v_mul_f32_e64 v144, v52, v4
	v_mul_f32_e64 v145, v53, v5
	v_pk_mul_f32 v[142:143], v[50:51], v[2:3]
	v_lshl_add_u64 v[176:177], s[0:1], 0, v[160:161]
	v_mfma_f32_16x16x32_bf16 v[2:5], v[26:29], v[30:33], v[122:125]
	v_lshl_add_u64 v[178:179], s[0:1], 0, v[0:1]
	v_cvt_pk_bf16_f32 v191, v144, v145
	v_cvt_pk_bf16_f32 v190, v142, v143
	v_mfma_f32_16x16x32_bf16 v[146:149], v[42:45], v[186:189], v[10:13]
	s_waitcnt vmcnt(1)
	v_mfma_f32_16x16x16_bf16 v[186:189], v[112:113], v[96:97], 0
	s_nop 1
	v_mul_f32_e64 v124, v36, v4
	v_mul_f32_e64 v125, v37, v5
	v_pk_mul_f32 v[122:123], v[34:35], v[2:3]
	v_cvt_pk_bf16_f32 v193, v124, v125
	v_mfma_f32_16x16x32_bf16 v[2:5], v[14:17], v[30:33], v[118:121]
	v_cvt_pk_bf16_f32 v192, v122, v123
	v_pk_add_f32 v[188:189], v[188:189], 0 op_sel_hi:[1,0]
	v_pk_add_f32 v[186:187], v[186:187], 0 op_sel_hi:[1,0]
	s_nop 4
	v_pk_mul_f32 v[120:121], v[24:25], v[4:5]
	v_pk_mul_f32 v[118:119], v[22:23], v[2:3]
	v_mfma_f32_16x16x32_bf16 v[2:5], v[6:9], v[30:33], v[114:117]
	v_lshl_add_u64 v[30:31], s[0:1], 0, v[152:153]
	v_add_co_u32_e32 v6, vcc, s20, v30
	s_mov_b32 s20, 0x46f9c000
	s_nop 0
	v_addc_co_u32_e32 v7, vcc, 0, v31, vcc
	s_nop 2
	v_pk_mul_f32 v[116:117], v[20:21], v[4:5]
	v_pk_mul_f32 v[114:115], v[18:19], v[2:3]
	global_load_dwordx4 v[2:5], v[6:7], off offset:1280
	global_load_dwordx4 v[10:13], v[6:7], off offset:2304
	global_load_dwordx4 v[46:49], v[6:7], off offset:3328
	v_add_co_u32_e32 v6, vcc, s20, v30
	s_mov_b32 s20, 0x46f9e000
	s_nop 0
	v_addc_co_u32_e32 v7, vcc, 0, v31, vcc
	v_add_co_u32_e32 v94, vcc, s29, v30
	global_load_dwordx4 v[42:45], v[6:7], off offset:256
	global_load_dwordx4 v[38:41], v[6:7], off offset:1280
	global_load_dwordx4 v[26:29], v[6:7], off offset:2304
	global_load_dwordx4 v[14:17], v[6:7], off offset:3328
	v_addc_co_u32_e32 v95, vcc, 0, v31, vcc
	v_add_co_u32_e32 v18, vcc, s20, v176
	global_load_dwordx4 v[6:9], v[94:95], off offset:256
	s_nop 0
	v_addc_co_u32_e32 v19, vcc, 0, v177, vcc
	global_load_dwordx4 v[50:53], v[18:19], off offset:256
	global_load_dwordx4 v[34:37], v[18:19], off offset:320
	global_load_dwordx4 v[22:25], v[18:19], off offset:384
	s_nop 0
	global_load_dwordx4 v[18:21], v[18:19], off offset:448
	v_add_co_u32_e32 v32, vcc, s29, v178
	v_cvt_pk_bf16_f32 v197, v120, v121
	s_nop 0
	v_addc_co_u32_e32 v33, vcc, 0, v179, vcc
	global_load_dwordx2 v[32:33], v[32:33], off offset:1280
	s_nop 0
	global_load_dwordx4 v[102:105], v[94:95], off offset:3328
	v_cndmask_b32_e64 v94, v146, v147, s[4:5]
	v_cndmask_b32_e64 v95, v148, v149, s[4:5]
	v_cvt_pk_bf16_f32 v196, v118, v119
	v_mov_b32_dpp v94, v94 quad_perm:[1,0,3,2] row_mask:0xf bank_mask:0xf bound_ctrl:1
	v_mov_b32_dpp v95, v95 quad_perm:[1,0,3,2] row_mask:0xf bank_mask:0xf bound_ctrl:1
	v_cndmask_b32_e64 v146, v94, v146, s[4:5]
	v_cndmask_b32_e64 v94, v147, v94, s[4:5]
	v_cndmask_b32_e64 v147, v95, v148, s[4:5]
	v_cndmask_b32_e64 v95, v149, v95, s[4:5]
	v_cndmask_b32_e64 v148, v146, v147, s[6:7]
	v_cndmask_b32_e64 v149, v94, v95, s[6:7]
	v_cvt_pk_bf16_f32 v199, v116, v117
	v_mov_b32_dpp v148, v148 quad_perm:[2,3,0,1] row_mask:0xf bank_mask:0xf bound_ctrl:1
	v_mov_b32_dpp v149, v149 quad_perm:[2,3,0,1] row_mask:0xf bank_mask:0xf bound_ctrl:1
	v_cndmask_b32_e64 v146, v148, v146, s[6:7]
	v_cndmask_b32_e64 v94, v149, v94, s[6:7]
	v_cndmask_b32_e64 v147, v147, v148, s[6:7]
	v_cndmask_b32_e64 v95, v95, v149, s[6:7]
	v_cvt_pk_bf16_f32 v95, v147, v95
	v_cvt_pk_bf16_f32 v94, v146, v94
	v_lshlrev_b64 v[146:147], 11, v[174:175]
	v_lshl_add_u64 v[146:147], v[172:173], 0, v[146:147]
	global_store_dwordx2 v[146:147], v[94:95], off
	v_mfma_f32_16x16x16_bf16 v[146:149], v[110:111], v[96:97], 0
	v_cvt_pk_bf16_f32 v198, v114, v115
	s_nop 6
	v_pk_add_f32 v[148:149], v[148:149], 0 op_sel_hi:[1,0]
	v_pk_add_f32 v[146:147], v[146:147], 0 op_sel_hi:[1,0]
	s_nop 1
	v_mfma_f32_16x16x32_bf16 v[146:149], v[54:57], v[190:193], v[146:149]
	v_mfma_f32_16x16x32_bf16 v[200:203], v[58:61], v[196:199], v[146:149]
	v_mfma_f32_16x16x32_bf16 v[146:149], v[62:65], v[190:193], v[186:189]
	v_mfma_f32_16x16x32_bf16 v[146:149], v[66:69], v[196:199], v[146:149]
	s_nop 5
	v_cvt_pk_bf16_f32 v95, v202, v203
	v_cvt_pk_bf16_f32 v94, v200, v201
	s_nop 1
	v_mfma_f32_16x16x32_bf16 v[142:145], v[70:73], v[94:97], v[142:145]
	v_mfma_f32_16x16x32_bf16 v[122:125], v[74:77], v[94:97], v[122:125]
	v_mfma_f32_16x16x32_bf16 v[118:121], v[78:81], v[94:97], v[118:121]
	v_mfma_f32_16x16x32_bf16 v[114:117], v[82:85], v[94:97], v[114:117]
	v_mov_b64_e32 v[86:87], v[138:139]
	v_mov_b64_e32 v[90:91], v[134:135]
	v_mov_b64_e32 v[98:99], v[130:131]
	v_mov_b64_e32 v[106:107], v[126:127]
	v_mov_b64_e32 v[88:89], v[140:141]
	v_mov_b64_e32 v[92:93], v[136:137]
	v_mov_b64_e32 v[100:101], v[132:133]
	v_mov_b64_e32 v[108:109], v[128:129]
	s_cbranch_scc1 .LBB0_134
	v_add_co_u32_e32 v66, vcc, 0x46f9e000, v30
	s_nop 1
	v_addc_co_u32_e32 v67, vcc, 0, v31, vcc
	v_add_co_u32_e32 v82, vcc, 0x46f9f000, v30
	global_load_dwordx4 v[54:57], v[66:67], off offset:512
	global_load_dwordx4 v[58:61], v[66:67], off offset:1536
	global_load_dwordx4 v[62:65], v[66:67], off offset:2560
	s_nop 0
	global_load_dwordx4 v[66:69], v[66:67], off offset:3584
	v_addc_co_u32_e32 v83, vcc, 0, v31, vcc
	v_add_co_u32_e32 v94, vcc, 0x46fa0000, v176
	global_load_dwordx4 v[70:73], v[82:83], off offset:512
	global_load_dwordx4 v[74:77], v[82:83], off offset:1536
	global_load_dwordx4 v[78:81], v[82:83], off offset:2560
	s_nop 0
	global_load_dwordx4 v[82:85], v[82:83], off offset:3584
	v_addc_co_u32_e32 v95, vcc, 0, v177, vcc
	global_load_dwordx4 v[126:129], v[94:95], off offset:3584
	global_load_dwordx4 v[130:133], v[94:95], off offset:3648
	global_load_dwordx4 v[134:137], v[94:95], off offset:3712
	global_load_dwordx4 v[138:141], v[94:95], off offset:3776
	v_add_co_u32_e32 v94, vcc, 0x46fa0000, v178
	s_nop 1
	v_addc_co_u32_e32 v95, vcc, 0, v179, vcc
	v_add_co_u32_e32 v30, vcc, 0x46fa0000, v30
	s_nop 1
	v_addc_co_u32_e32 v31, vcc, 0, v31, vcc
	global_load_dwordx2 v[96:97], v[94:95], off offset:512
	global_load_dwordx4 v[110:113], v[30:31], off offset:2560

; __device__ __forceinline__ void ph_wkv2(const Params& p, int jl, int lane, int wave) {
;     ...
;     if (wave >= 2) {
;         const int gws = blockIdx.x * (NWAVES - 2) + (wave - 2), NGWS = gridDim.x * (NWAVES - 2);
;         constexpr int UB = 4;
.LBB0_190:
	v_readlane_b32 s36, v254, 49
	v_readlane_b32 s44, v254, 60
	v_readlane_b32 s37, v254, 50
	v_readlane_b32 s58, v255, 10
	v_readlane_b32 s59, v255, 11
	s_mov_b32 s29, 0x46f9d000
	v_readlane_b32 s45, v254, 61
	v_readlane_b32 s46, v254, 62
	v_readlane_b32 s47, v254, 63
	v_readlane_b32 s48, v255, 0
	v_readlane_b32 s49, v255, 1
	v_readlane_b32 s50, v255, 2
	v_readlane_b32 s51, v255, 3
	v_readlane_b32 s52, v255, 4
	v_readlane_b32 s53, v255, 5
	v_readlane_b32 s54, v255, 6
	v_readlane_b32 s55, v255, 7
	v_readlane_b32 s56, v255, 8
	v_readlane_b32 s57, v255, 9
	v_readlane_b32 s0, v255, 15
	s_cmp_lg_u32 s0, 2
	s_cbranch_scc1 .Lw2pf_done
	v_readlane_b32 s0, v252, 46
	s_lshr_b32 s0, s0, 2
	s_mul_i32 s0, s0, 0x16ad00
	v_readlane_b32 s2, v252, 47
	v_readlane_b32 s3, v252, 48
	s_add_u32 s2, s2, s0
	s_addc_u32 s3, s3, 0
	v_mbcnt_lo_u32_b32 v0, -1, 0
	v_mbcnt_hi_u32_b32 v0, -1, v0
	v_lshlrev_b32_e32 v0, 7, v0
	s_mov_b32 s4, 0
	s_mov_b32 s5, 0
.Lw2pf_poll:
	ds_read_b32 v3, v1
	s_waitcnt lgkmcnt(0)
	v_readfirstlane_b32 s6, v3
	s_cmpk_gt_u32 s6, 0x80
	s_cbranch_scc1 .Lw2pf_done
	s_add_i32 s8, s6, 3
	s_mul_i32 s8, s8, 0x2d00
	s_and_b32 s8, s8, 0xffffe000
	s_max_u32 s4, s4, s8
	s_add_i32 s7, s6, 6
	s_mul_i32 s7, s7, 0x2d00
	s_cmp_ge_u32 s4, s7
	s_cbranch_scc1 .Lw2pf_sleep
	s_add_i32 s7, s4, 0x10000
	s_min_u32 s7, s7, 0x16ad00
.Lw2pf_issue:
	v_add_u32_e32 v4, s4, v0
	v_min_u32_e32 v4, 0x16acfc, v4
	global_load_dword v5, v4, s[2:3]
	s_add_i32 s4, s4, 0x2000
	s_cmp_lt_u32 s4, s7
	s_cbranch_scc1 .Lw2pf_issue
	s_cmp_ge_u32 s4, 0x16ad00
	s_cbranch_scc1 .Lw2pf_done
.Lw2pf_sleep:
	s_add_i32 s5, s5, 1
	s_cmp_gt_u32 s5, 0x8000
	s_cbranch_scc1 .Lw2pf_done
	s_sleep 2
	s_branch .Lw2pf_poll
.Lw2pf_done:
.LBB0_191:
	s_mov_b64 s[0:1], 0
